# v18 + merge attention part: all 8-9 token rows of a wave and the gain requested in front of the loop (was 2 serial row loads + 4 gain loads per trip), rows rotated through registers
# baseline (speedup 1.0000x reference)
; #define GAS __attribute__((address_space(1)))
; __device__ __forceinline__ void merge_phase(Frame& F, int l, bool with_ctx) {
;     ...
;         for (int tk = F.wave; tk < TI; tk += NWAVES) {
;             const size_t row = (size_t)(tok0 + tk);
;             const v4u r0 = *(const GAS v4u*)(A + row * 1024 + 8 * F.lane), r1 = *(const GAS v4u*)(A + row * 1024 + 512 + 8 * F.lane);
;             float v[16];
;             v[0] = bf2f(r0.x & 0xffff); v[1] = bf2f(r0.x >> 16); v[2] = bf2f(r0.y & 0xffff); v[3] = bf2f(r0.y >> 16); v[4] = bf2f(r0.z & 0xffff); v[5] = bf2f(r0.z >> 16); v[6] = bf2f(r0.w & 0xffff); v[7] = bf2f(r0.w >> 16);
;             v[8] = bf2f(r1.x & 0xffff); v[9] = bf2f(r1.x >> 16); v[10] = bf2f(r1.y & 0xffff); v[11] = bf2f(r1.y >> 16); v[12] = bf2f(r1.z & 0xffff); v[13] = bf2f(r1.z >> 16); v[14] = bf2f(r1.w & 0xffff); v[15] = bf2f(r1.w >> 16);
;             float ss = 0.f;
; #pragma unroll
;             for (int j = 0; j < 16; ++j) ss += v[j] * v[j];
;             const float rstd = 1.0f / sqrtf(wave_sum(ss, F.lane) * (1.0f / NAW) + EPS);
;             const f32x4 g0 = *(const GAS f32x4*)(gain + 8 * F.lane), g1 = *(const GAS f32x4*)(gain + 8 * F.lane + 4), g2 = *(const GAS f32x4*)(gain + 512 + 8 * F.lane), g3 = *(const GAS f32x4*)(gain + 512 + 8 * F.lane + 4);
.LBB0_1074:
	v_cndmask_b32_e64 v0, 0, 1, s[12:13]
	v_cmp_ne_u32_e64 s[4:5], 1, v0
	s_andn2_b64 vcc, exec, s[12:13]
	s_cbranch_vccnz .LBB0_1077
	s_ashr_i32 s21, s20, 31
	s_lshl_b64 s[6:7], s[20:21], 12
	v_readlane_b32 s26, v255, 43
	v_readlane_b32 s27, v255, 44
	s_add_u32 s24, s26, s6
	s_addc_u32 s25, s27, s7
	s_lshl_b64 s[6:7], s[20:21], 11
	s_add_u32 s26, s26, s6
	s_addc_u32 s27, s27, s7
	s_mov_b32 s3, s37
	global_load_dwordx4 v[74:77], v[10:11], off offset:16
	global_load_dwordx4 v[78:81], v[10:11], off
	global_load_dwordx4 v[82:85], v[10:11], off offset:2064
	global_load_dwordx4 v[86:89], v[10:11], off offset:2048
	v_lshl_add_u64 v[24:25], s[26:27], 0, v[14:15]
	s_mov_b32 s6, 0x44900000
	v_add_co_u32_e32 v28, vcc, s6, v24
	s_nop 0
	v_addc_co_u32_e32 v29, vcc, 0, v25, vcc
	global_load_dwordx4 v[94:97], v[28:29], off offset:1024
	global_load_dwordx4 v[90:93], v[28:29], off
	v_add_co_u32_e32 v28, vcc, 0x4000, v28
	s_nop 0
	v_addc_co_u32_e32 v29, vcc, 0, v29, vcc
	global_load_dwordx4 v[102:105], v[28:29], off offset:1024
	global_load_dwordx4 v[98:101], v[28:29], off
	v_add_co_u32_e32 v28, vcc, 0x4000, v28
	s_nop 0
	v_addc_co_u32_e32 v29, vcc, 0, v29, vcc
	global_load_dwordx4 v[110:113], v[28:29], off offset:1024
	global_load_dwordx4 v[106:109], v[28:29], off
	v_add_co_u32_e32 v28, vcc, 0x4000, v28
	s_nop 0
	v_addc_co_u32_e32 v29, vcc, 0, v29, vcc
	global_load_dwordx4 v[118:121], v[28:29], off offset:1024
	global_load_dwordx4 v[114:117], v[28:29], off
	v_add_co_u32_e32 v28, vcc, 0x4000, v28
	s_nop 0
	v_addc_co_u32_e32 v29, vcc, 0, v29, vcc
	global_load_dwordx4 v[126:129], v[28:29], off offset:1024
	global_load_dwordx4 v[122:125], v[28:29], off
	v_add_co_u32_e32 v28, vcc, 0x4000, v28
	s_nop 0
	v_addc_co_u32_e32 v29, vcc, 0, v29, vcc
	global_load_dwordx4 v[134:137], v[28:29], off offset:1024
	global_load_dwordx4 v[130:133], v[28:29], off
	v_add_co_u32_e32 v28, vcc, 0x4000, v28
	s_nop 0
	v_addc_co_u32_e32 v29, vcc, 0, v29, vcc
	global_load_dwordx4 v[142:145], v[28:29], off offset:1024
	global_load_dwordx4 v[138:141], v[28:29], off
	v_add_co_u32_e32 v28, vcc, 0x4000, v28
	s_nop 0
	v_addc_co_u32_e32 v29, vcc, 0, v29, vcc
	global_load_dwordx4 v[150:153], v[28:29], off offset:1024
	global_load_dwordx4 v[146:149], v[28:29], off
	v_add_co_u32_e32 v28, vcc, 0x4000, v28
	s_nop 0
	v_addc_co_u32_e32 v29, vcc, 0, v29, vcc
	s_add_i32 s6, s3, 64
	s_cmp_lt_i32 s6, s31
	s_cbranch_scc0 .Lma_ld_done
	global_load_dwordx4 v[158:161], v[28:29], off offset:1024
	global_load_dwordx4 v[154:157], v[28:29], off

; #define GAS __attribute__((address_space(1)))
; __device__ __forceinline__ void merge_phase(Frame& F, int l, bool with_ctx) {
;     ...
;         for (int tk = F.wave; tk < TI; tk += NWAVES) {
;             const size_t row = (size_t)(tok0 + tk);
;             const v4u r0 = *(const GAS v4u*)(A + row * 1024 + 8 * F.lane), r1 = *(const GAS v4u*)(A + row * 1024 + 512 + 8 * F.lane);
;             float v[16];
;             v[0] = bf2f(r0.x & 0xffff); v[1] = bf2f(r0.x >> 16); v[2] = bf2f(r0.y & 0xffff); v[3] = bf2f(r0.y >> 16); v[4] = bf2f(r0.z & 0xffff); v[5] = bf2f(r0.z >> 16); v[6] = bf2f(r0.w & 0xffff); v[7] = bf2f(r0.w >> 16);
;             v[8] = bf2f(r1.x & 0xffff); v[9] = bf2f(r1.x >> 16); v[10] = bf2f(r1.y & 0xffff); v[11] = bf2f(r1.y >> 16); v[12] = bf2f(r1.z & 0xffff); v[13] = bf2f(r1.z >> 16); v[14] = bf2f(r1.w & 0xffff); v[15] = bf2f(r1.w >> 16);
;             float ss = 0.f;
; #pragma unroll
;             for (int j = 0; j < 16; ++j) ss += v[j] * v[j];
;             const float rstd = 1.0f / sqrtf(wave_sum(ss, F.lane) * (1.0f / NAW) + EPS);
.LBB0_1076:
	v_mov_b32_e32 v0, v74
	v_mov_b32_e32 v1, v75
	v_mov_b32_e32 v2, v76
	v_mov_b32_e32 v3, v77
	v_mov_b32_e32 v4, v78
	v_mov_b32_e32 v5, v79
	v_mov_b32_e32 v6, v80
	v_mov_b32_e32 v7, v81
	v_mov_b32_e32 v16, v82
	v_mov_b32_e32 v17, v83
	v_mov_b32_e32 v18, v84
	v_mov_b32_e32 v19, v85
	v_mov_b32_e32 v20, v86
	v_mov_b32_e32 v21, v87
	v_mov_b32_e32 v22, v88
	v_mov_b32_e32 v23, v89
	v_mov_b32_e32 v24, v94
	v_mov_b32_e32 v25, v95
	v_mov_b32_e32 v26, v96
	v_mov_b32_e32 v27, v97
	s_add_i32 s3, s3, 8
	v_mov_b32_e32 v68, v4
	v_mov_b32_e32 v69, v6
	v_mov_b32_e32 v39, v22
	v_mov_b32_e32 v22, v21
	v_mov_b32_e32 v38, v20
	v_lshlrev_b32_e32 v21, 16, v27
	v_and_b32_e32 v41, 0xffff0000, v27
	v_lshlrev_b32_e32 v31, 16, v25
	v_lshlrev_b32_e32 v30, 16, v24
	v_and_b32_e32 v33, 0xffff0000, v25
	v_and_b32_e32 v32, 0xffff0000, v24
	v_mov_b32_e32 v24, v41
	v_mov_b32_e32 v25, v21
	v_lshlrev_b32_e32 v20, 16, v26
	v_and_b32_e32 v40, 0xffff0000, v26
	v_pk_mul_f32 v[62:63], v[24:25], v[24:25]
	v_mov_b32_e32 v24, v90
	v_mov_b32_e32 v25, v91
	v_mov_b32_e32 v26, v92
	v_mov_b32_e32 v27, v93
	v_mov_b32_e32 v6, v5
	v_pk_mul_f32 v[34:35], v[30:31], v[30:31]
	v_pk_mul_f32 v[36:37], v[32:33], v[32:33]
	v_lshlrev_b32_e32 v29, 16, v25
	v_lshlrev_b32_e32 v28, 16, v24
	v_and_b32_e32 v25, 0xffff0000, v25
	v_and_b32_e32 v24, 0xffff0000, v24
	v_pk_mul_f32 v[64:65], v[28:29], v[28:29]
	v_pk_mul_f32 v[66:67], v[24:25], v[24:25]
	v_lshlrev_b32_e32 v5, 16, v27
	v_add_f32_e32 v61, v64, v66
	v_lshlrev_b32_e32 v4, 16, v26
	v_add_f32_e32 v61, v65, v61
	v_and_b32_e32 v27, 0xffff0000, v27
	v_and_b32_e32 v26, 0xffff0000, v26
	v_pk_mul_f32 v[70:71], v[4:5], v[4:5]
	v_add_f32_e32 v61, v67, v61
	v_pk_mul_f32 v[72:73], v[26:27], v[26:27]
	v_add_f32_e32 v61, v70, v61
	v_add_f32_e32 v61, v72, v61
	v_add_f32_e32 v61, v71, v61
	v_add_f32_e32 v61, v73, v61
	v_add_f32_e32 v34, v34, v61
	v_add_f32_e32 v34, v36, v34
	v_add_f32_e32 v34, v35, v34
	v_add_f32_e32 v34, v37, v34
	v_fmac_f32_e32 v34, v20, v20
	v_fmac_f32_e32 v34, v40, v40
	v_add_f32_e32 v34, v63, v34
	v_add_f32_e32 v34, v62, v34
	ds_bpermute_b32 v35, v45, v34
	s_waitcnt lgkmcnt(0)
	v_add_f32_e32 v34, v34, v35
	ds_bpermute_b32 v35, v46, v34
	s_waitcnt lgkmcnt(0)
	v_add_f32_e32 v34, v34, v35
	ds_bpermute_b32 v35, v47, v34
	s_waitcnt lgkmcnt(0)
	v_add_f32_e32 v34, v34, v35
	ds_bpermute_b32 v35, v48, v34
	s_waitcnt lgkmcnt(0)
	v_add_f32_e32 v34, v34, v35
	ds_bpermute_b32 v35, v49, v34
	s_waitcnt lgkmcnt(0)
	v_add_f32_e32 v34, v34, v35
	ds_bpermute_b32 v35, v50, v34
	s_waitcnt lgkmcnt(0)
; #define GAS __attribute__((address_space(1)))
; __device__ __forceinline__ unsigned pk2(float lo, float hi) { return f2bf(lo) | (f2bf(hi) << 16); }
; __device__ __forceinline__ void merge_phase(Frame& F, int l, bool with_ctx) {
;     ...
;             const float rstd = 1.0f / sqrtf(wave_sum(ss, F.lane) * (1.0f / NAW) + EPS);
;             const f32x4 g0 = *(const GAS f32x4*)(gain + 8 * F.lane), g1 = *(const GAS f32x4*)(gain + 8 * F.lane + 4), g2 = *(const GAS f32x4*)(gain + 512 + 8 * F.lane), g3 = *(const GAS f32x4*)(gain + 512 + 8 * F.lane + 4);
;             v4u o0, o1;
;             o0.x = pk2(v[0] * rstd * g0.x, v[1] * rstd * g0.y); o0.y = pk2(v[2] * rstd * g0.z, v[3] * rstd * g0.w); o0.z = pk2(v[4] * rstd * g1.x, v[5] * rstd * g1.y); o0.w = pk2(v[6] * rstd * g1.z, v[7] * rstd * g1.w);
;             o1.x = pk2(v[8] * rstd * g2.x, v[9] * rstd * g2.y); o1.y = pk2(v[10] * rstd * g2.z, v[11] * rstd * g2.w); o1.z = pk2(v[12] * rstd * g3.x, v[13] * rstd * g3.y); o1.w = pk2(v[14] * rstd * g3.z, v[15] * rstd * g3.w);
;             *(GAS v4u*)(H + row * DM + 8 * F.lane) = o0; *(GAS v4u*)(H + row * DM + 512 + 8 * F.lane) = o1;
;         }
	v_add_f32_e32 v34, v34, v35
	v_fmamk_f32 v34, v34, 0x3a800000, v212
	v_cmp_gt_f32_e32 vcc, s60, v34
	v_mul_f32_e32 v35, 0x4f800000, v34
	s_nop 0
	v_cndmask_b32_e32 v34, v34, v35, vcc
	v_sqrt_f32_e32 v35, v34
	s_nop 0
	v_add_u32_e32 v36, -1, v35
	v_fma_f32 v37, -v36, v35, v34
	v_cmp_ge_f32_e64 s[6:7], 0, v37
	v_add_u32_e32 v37, 1, v35
	s_nop 0
	v_cndmask_b32_e64 v36, v35, v36, s[6:7]
	v_fma_f32 v35, -v37, v35, v34
	v_cmp_lt_f32_e64 s[6:7], 0, v35
	s_nop 1
	v_cndmask_b32_e64 v35, v36, v37, s[6:7]
	v_mul_f32_e32 v36, 0x37800000, v35
	v_cndmask_b32_e32 v35, v35, v36, vcc
	v_cmp_class_f32_e32 vcc, v34, v213
	s_nop 1
	v_cndmask_b32_e32 v34, v35, v34, vcc
	v_div_scale_f32 v35, s[6:7], v34, v34, 1.0
	v_rcp_f32_e32 v36, v35
	s_brev_b32 s6, 4
	v_fma_f32 v37, -v35, v36, 1.0
	v_fmac_f32_e32 v36, v37, v36
	v_div_scale_f32 v37, vcc, 1.0, v34, 1.0
	v_mul_f32_e32 v61, v37, v36
	v_fma_f32 v62, -v35, v61, v37
	v_fmac_f32_e32 v61, v62, v36
	v_fma_f32 v35, -v35, v61, v37
	v_div_fmas_f32 v35, v35, v36, v61
	v_div_fixup_f32 v34, v35, v34, 1.0
	v_pk_mul_f32 v[24:25], v[34:35], v[24:25] op_sel_hi:[0,1]
	v_pk_mul_f32 v[6:7], v[6:7], v[24:25]
	v_pk_mul_f32 v[4:5], v[34:35], v[4:5] op_sel_hi:[0,1]
	v_mov_b32_e32 v24, v0
	v_mov_b32_e32 v25, v2
	v_pk_mul_f32 v[4:5], v[24:25], v[4:5]
	v_pk_mul_f32 v[24:25], v[34:35], v[26:27] op_sel_hi:[0,1]
	v_mov_b32_e32 v2, v1
	v_pk_mul_f32 v[28:29], v[34:35], v[28:29] op_sel_hi:[0,1]
	v_pk_mul_f32 v[0:1], v[2:3], v[24:25]
	v_pk_mul_f32 v[28:29], v[68:69], v[28:29]
	v_bfe_u32 v2, v1, 16, 1
	v_bfe_u32 v3, v0, 16, 1
	v_bfe_u32 v24, v7, 16, 1
	v_bfe_u32 v25, v6, 16, 1
	v_add3_u32 v6, v6, v25, s61
	v_add3_u32 v7, v7, v24, s61
	v_add3_u32 v0, v0, v3, s61
	v_add3_u32 v1, v1, v2, s61
	v_bfe_u32 v2, v28, 16, 1
	v_bfe_u32 v3, v29, 16, 1
	v_bfe_u32 v24, v4, 16, 1
	v_bfe_u32 v25, v5, 16, 1
	v_add3_u32 v5, v5, v25, s61
	v_add3_u32 v4, v4, v24, s61
	v_add3_u32 v3, v29, v3, s61
	v_add3_u32 v2, v28, v2, s61
	v_lshrrev_b32_e32 v24, 16, v2
	v_lshrrev_b32_e32 v25, 16, v3
	v_lshrrev_b32_e32 v2, 16, v4
	v_lshrrev_b32_e32 v3, 16, v5
	v_and_or_b32 v3, v1, s86, v3
	v_and_or_b32 v2, v0, s86, v2
	v_and_or_b32 v1, v7, s86, v25
	v_and_or_b32 v0, v6, s86, v24
	v_pk_mul_f32 v[6:7], v[34:35], v[32:33] op_sel_hi:[0,1]
	v_pk_mul_f32 v[6:7], v[22:23], v[6:7]
	v_pk_mul_f32 v[20:21], v[34:35], v[20:21] op_sel_hi:[0,1]
	v_mov_b32_e32 v22, v16
	v_mov_b32_e32 v23, v18
	v_pk_mul_f32 v[20:21], v[22:23], v[20:21]
	v_pk_mul_f32 v[22:23], v[34:35], v[40:41] op_sel_hi:[0,1]
	v_mov_b32_e32 v18, v17
	v_pk_mul_f32 v[16:17], v[18:19], v[22:23]
	v_pk_mul_f32 v[4:5], v[34:35], v[30:31] op_sel_hi:[0,1]
	v_bfe_u32 v18, v17, 16, 1
	v_bfe_u32 v19, v16, 16, 1
	v_bfe_u32 v22, v7, 16, 1
	v_bfe_u32 v23, v6, 16, 1
	v_pk_mul_f32 v[4:5], v[38:39], v[4:5]
	v_add3_u32 v23, v6, v23, s61
	v_add3_u32 v22, v7, v22, s61
	v_add3_u32 v6, v16, v19, s61
	v_add3_u32 v7, v17, v18, s61
	v_bfe_u32 v18, v20, 16, 1
	v_bfe_u32 v19, v21, 16, 1
	v_bfe_u32 v16, v4, 16, 1
	v_bfe_u32 v17, v5, 16, 1
	v_add3_u32 v19, v21, v19, s61
	v_add3_u32 v18, v20, v18, s61
	v_add3_u32 v5, v5, v17, s61
	v_add3_u32 v4, v4, v16, s61
	v_lshrrev_b32_e32 v16, 16, v18
	v_lshrrev_b32_e32 v17, 16, v19
	v_and_or_b32 v7, v7, s86, v17
	v_and_or_b32 v6, v6, s86, v16
	v_lshl_add_u64 v[16:17], s[24:25], 0, v[14:15]
	s_add_u32 s24, s24, 0x8000
	s_addc_u32 s25, s25, 0
	s_add_u32 s26, s26, 0x4000
	v_add_co_u32_e32 v16, vcc, s6, v16
	s_addc_u32 s27, s27, 0
	v_lshrrev_b32_e32 v4, 16, v4
	v_lshrrev_b32_e32 v5, 16, v5
	v_addc_co_u32_e32 v17, vcc, 0, v17, vcc
	s_cmp_ge_i32 s3, s31
	v_and_or_b32 v5, v22, s86, v5
	v_and_or_b32 v4, v23, s86, v4
	global_store_dwordx4 v[16:17], v[0:3], off
	global_store_dwordx4 v[16:17], v[4:7], off offset:1024
	v_mov_b32_e32 v90, v98
	v_mov_b32_e32 v91, v99
	v_mov_b32_e32 v92, v100
	v_mov_b32_e32 v93, v101
	v_mov_b32_e32 v94, v102
	v_mov_b32_e32 v95, v103
	v_mov_b32_e32 v96, v104
	v_mov_b32_e32 v97, v105
	v_mov_b32_e32 v98, v106
	v_mov_b32_e32 v99, v107
	v_mov_b32_e32 v100, v108
	v_mov_b32_e32 v101, v109
	v_mov_b32_e32 v102, v110
	v_mov_b32_e32 v103, v111
	v_mov_b32_e32 v104, v112
	v_mov_b32_e32 v105, v113
	v_mov_b32_e32 v106, v114
	v_mov_b32_e32 v107, v115
	v_mov_b32_e32 v108, v116
	v_mov_b32_e32 v109, v117
	v_mov_b32_e32 v110, v118
	v_mov_b32_e32 v111, v119
	v_mov_b32_e32 v112, v120
	v_mov_b32_e32 v113, v121
	v_mov_b32_e32 v114, v122
	v_mov_b32_e32 v115, v123
	v_mov_b32_e32 v116, v124
	v_mov_b32_e32 v117, v125
	v_mov_b32_e32 v118, v126
	v_mov_b32_e32 v119, v127
	v_mov_b32_e32 v120, v128
	v_mov_b32_e32 v121, v129
	v_mov_b32_e32 v122, v130
	v_mov_b32_e32 v123, v131
	v_mov_b32_e32 v124, v132
	v_mov_b32_e32 v125, v133
	v_mov_b32_e32 v126, v134
	v_mov_b32_e32 v127, v135
	v_mov_b32_e32 v128, v136
	v_mov_b32_e32 v129, v137
	v_mov_b32_e32 v130, v138
	v_mov_b32_e32 v131, v139
	v_mov_b32_e32 v132, v140
	v_mov_b32_e32 v133, v141
	v_mov_b32_e32 v134, v142
	v_mov_b32_e32 v135, v143
	v_mov_b32_e32 v136, v144
	v_mov_b32_e32 v137, v145
	v_mov_b32_e32 v138, v146
	v_mov_b32_e32 v139, v147
	v_mov_b32_e32 v140, v148
	v_mov_b32_e32 v141, v149
	v_mov_b32_e32 v142, v150
	v_mov_b32_e32 v143, v151
	v_mov_b32_e32 v144, v152
	v_mov_b32_e32 v145, v153
	v_mov_b32_e32 v146, v154
	v_mov_b32_e32 v147, v155
	v_mov_b32_e32 v148, v156
	v_mov_b32_e32 v149, v157
	v_mov_b32_e32 v150, v158
	v_mov_b32_e32 v151, v159
	v_mov_b32_e32 v152, v160
	v_mov_b32_e32 v153, v161
	s_cbranch_scc0 .LBB0_1076
